# XCD-local barriers on the row-local seams (hprep/FFN-up/FFN-down/in-proj, out-proj chain), modnorm pre-pass rows assigned per XCD
# speedup vs baseline: 1.0421x; 1.0242x over previous
.LBB0_2:
	s_waitcnt lgkmcnt(0)
	v_writelane_b32 v248, s4, 2
	s_nop 1
	v_writelane_b32 v248, s5, 3
	s_or_b64 exec, exec, s[0:1]
	s_barrier
	s_load_dwordx2 s[0:1], s[84:85], 0x108
	s_getreg_b32 s4, hwreg(HW_REG_XCC_ID, 0, 4)
	v_mov_b32 v1, v194
	s_waitcnt lgkmcnt(0)
	s_add_u32 s2, s0, 0x7c74100
	s_addc_u32 s3, s1, 0
	s_and_b32 s8, s4, 15
	v_cmp_eq_u32_e32 vcc, 0, v1
	s_and_saveexec_b64 s[4:5], vcc
	s_cbranch_execz .LBB0_5
	s_mov_b64 s[6:7], exec
	v_mbcnt_lo_u32_b32 v1, s6, 0
	v_mbcnt_hi_u32_b32 v1, s7, v1
	v_cmp_eq_u32_e32 vcc, 0, v1
	s_and_b64 s[10:11], exec, vcc
	s_mov_b64 exec, s[10:11]
	s_cbranch_execz .LBB0_5
	s_lshl_b32 s9, s8, 8
	s_bcnt1_i32_b64 s6, s[6:7]
	v_mov_b32_e32 v1, s9
	v_mov_b32_e32 v2, s6
	global_atomic_add v1, v2, s[2:3] offset:1024
	s_and_b32 s9, s82, 7
	s_lshl_b32 s9, s9, 2
	s_add_i32 s9, s9, 0x36b0
	s_lshl_b32 s6, 1, s8
	v_mov_b32_e32 v1, s9
	v_mov_b32_e32 v2, s6
	global_atomic_or v1, v2, s[2:3]

.LBB0_47:
	s_nop 0
	v_readlane_b32 s0, v246, 25
	s_cmp_eq_u32 s0, 12
	s_cbranch_scc1 .LBB0_8
	v_readlane_b32 s0, v248, 4
	s_cmp_le_i32 s96, s0
	v_readlane_b32 s1, v248, 5
	s_cbranch_scc1 .LBB0_123
	v_readlane_b32 s8, v248, 6
	v_readlane_b32 s9, v248, 7
	s_mov_b64 s[0:1], -1
	s_and_b64 vcc, exec, s[8:9]
	s_cbranch_vccz .LBB0_109
	s_cmp_lg_u32 s96, 2
	s_cbranch_scc1 .Lhw_bar_scope
	s_load_dwordx2 s[8:9], s[84:85], 0x108
	v_and_b32_e32 v2, 7, v194
	v_lshlrev_b32_e32 v2, 2, v2
	s_waitcnt lgkmcnt(0)
	s_add_u32 s8, s8, 0x7c777b0
	s_addc_u32 s9, s9, 0
	global_load_dword v3, v2, s[8:9] sc1
	s_mov_b32 s6, 0
	s_mov_b32 s2, 1
	s_waitcnt vmcnt(0)
	v_readlane_b32 s8, v3, 0
	s_bcnt1_i32_b32 s9, s8
	s_cmp_eq_u32 s9, 1
	s_cselect_b32 s2, s2, 0
	s_or_b32 s6, s6, s8
	v_readlane_b32 s8, v3, 1
	s_bcnt1_i32_b32 s9, s8
	s_cmp_eq_u32 s9, 1
	s_cselect_b32 s2, s2, 0
	s_or_b32 s6, s6, s8
	v_readlane_b32 s8, v3, 2
	s_bcnt1_i32_b32 s9, s8
	s_cmp_eq_u32 s9, 1
	s_cselect_b32 s2, s2, 0
	s_or_b32 s6, s6, s8
	v_readlane_b32 s8, v3, 3
	s_bcnt1_i32_b32 s9, s8
	s_cmp_eq_u32 s9, 1
	s_cselect_b32 s2, s2, 0
	s_or_b32 s6, s6, s8
	v_readlane_b32 s8, v3, 4
	s_bcnt1_i32_b32 s9, s8
	s_cmp_eq_u32 s9, 1
	s_cselect_b32 s2, s2, 0
	s_or_b32 s6, s6, s8
	v_readlane_b32 s8, v3, 5
	s_bcnt1_i32_b32 s9, s8
	s_cmp_eq_u32 s9, 1
	s_cselect_b32 s2, s2, 0
	s_or_b32 s6, s6, s8
	v_readlane_b32 s8, v3, 6
	s_bcnt1_i32_b32 s9, s8
	s_cmp_eq_u32 s9, 1
	s_cselect_b32 s2, s2, 0
	s_or_b32 s6, s6, s8
	v_readlane_b32 s8, v3, 7
	s_bcnt1_i32_b32 s9, s8
	s_cmp_eq_u32 s9, 1
	s_cselect_b32 s2, s2, 0
	s_or_b32 s6, s6, s8
	s_cmpk_eq_u32 s6, 0xff
	s_cselect_b32 s2, s2, 0
	v_writelane_b32 v246, s2, 41
.Lhw_bar_scope:
	v_readlane_b32 s2, v246, 26
	s_movk_i32 s8, 0xe1e
	s_lshr_b32 s8, s8, s2
	v_readlane_b32 s6, v246, 41
	s_and_b32 s8, s8, 1
	s_and_b32 s8, s8, s6
	v_writelane_b32 v246, s8, 42
	s_waitcnt vmcnt(0)
	s_barrier
	v_mov_b32 v0, v194
	s_nop 0
	v_cmp_eq_u32_e32 vcc, 0, v0
	s_and_saveexec_b64 s[0:1], vcc
	s_cbranch_execz .LBB0_108
	s_waitcnt vmcnt(0) expcnt(0) lgkmcnt(0)
	ds_read_b32 v3, v1
	ds_read_b32 v0, v1 offset:4
	s_waitcnt lgkmcnt(1)
	v_cmp_ne_u32_e32 vcc, 0, v3
	s_cbranch_vccnz .LBB0_71
	s_mov_b32 s2, 1
	s_branch .LBB0_54

.LBB0_88:
	s_andn2_saveexec_b64 s[8:9], s[10:11]
	s_cbranch_execz .LBB0_108
	s_mov_b64 s[10:11], exec
	v_readlane_b32 s2, v246, 42
	s_cmp_lg_u32 s2, 0
	s_cbranch_scc1 .LBB0_105
	buffer_wbl2 sc1
	s_waitcnt lgkmcnt(0)
	s_waitcnt vmcnt(0)
	v_mbcnt_lo_u32_b32 v2, s10, 0
	v_mbcnt_hi_u32_b32 v2, s11, v2
	v_cmp_eq_u32_e32 vcc, 0, v2
	s_and_saveexec_b64 s[12:13], vcc
	s_cbranch_execz .LBB0_91
	s_bcnt1_i32_b64 s2, s[10:11]
	v_readlane_b32 s8, v247, 14
	v_mov_b32_e32 v3, s2
	v_readlane_b32 s9, v247, 15
	s_nop 4
	global_atomic_add v3, v1, v3, s[8:9] sc0

.LBB0_143:
	s_andn2_b64 vcc, exec, s[10:11]
	s_cbranch_vccnz .LBB0_148
	s_mov_b64 s[12:13], s[84:85]
	v_mov_b32 v0, v194
	v_readlane_b32 s2, v246, 16
	s_lshl_b32 s6, s83, 2
	s_lshl_b32 s2, s2, 7
	s_add_i32 s2, s2, s6
	s_waitcnt vmcnt(0) lgkmcnt(0)
	v_ashrrev_i32_e32 v2, 6, v0
	v_add_u32_e32 v2, s2, v2
	s_movk_i32 s2, 0x3000
	v_cmp_gt_i32_e32 vcc, s2, v2
	s_and_saveexec_b64 s[10:11], vcc
	v_readlane_b32 s20, v247, 53
	v_readlane_b32 s21, v247, 54
	s_movk_i32 s20, 0x100
	v_readlane_b32 s21, v246, 16
	s_lshl_b32 s21, s21, 7
	s_add_i32 s21, s21, 0x5ff
	s_mov_b32 s23, 0x800000
	s_movk_i32 s24, 0xfff
	v_readlane_b32 s26, v246, 28
	s_cbranch_execz .LBB0_147
	v_readlane_b32 s6, v246, 26
	s_cmp_eq_u32 s6, 3
	s_load_dwordx2 s[16:17], s[12:13], 0x108
	s_load_dwordx2 s[18:19], s[12:13], 0x60
	s_cselect_b32 s2, 1, 2
	s_cmp_lg_u32 s6, 0
	s_cselect_b32 s2, s2, 0
	v_readlane_b32 s6, v246, 27
	s_add_i32 s14, s2, s6
	s_ashr_i32 s15, s14, 31
	s_mul_i32 s9, s14, 0xc0000
	s_mul_hi_i32 s6, s14, 0xc0000
	s_waitcnt lgkmcnt(0)
	s_add_u32 s9, s16, s9
	s_addc_u32 s6, s17, s6
	s_add_u32 s12, s9, 0x7200000
	s_addc_u32 s13, s6, 0
	s_lshl_b64 s[14:15], s[14:15], 12
	s_add_u32 s18, s18, s14
	v_lshlrev_b32_e32 v0, 2, v0
	s_addc_u32 s19, s19, s15
	v_and_b32_e32 v0, 0xfc, v0
	s_add_u32 s14, s16, 0x7bc0000
	v_lshlrev_b32_e32 v6, 2, v0
	v_mov_b32_e32 v7, v1
	v_lshlrev_b32_e32 v8, 1, v0
	v_mov_b32_e32 v9, v1
	s_addc_u32 s15, s17, 0
	v_lshl_add_u64 v[4:5], s[18:19], 0, v[6:7]
	v_or_b32_e32 v10, 0x100, v0
	v_or_b32_e32 v12, 0x200, v0
	v_or_b32_e32 v14, 0x300, v0
	v_lshl_add_u64 v[6:7], s[16:17], 0, v[6:7]
	v_lshl_add_u64 v[8:9], s[16:17], 0, v[8:9]
	s_mov_b64 s[16:17], 0x14958100
	s_mul_i32 s2, s2, 3
	v_lshl_add_u64 v[8:9], v[8:9], 0, s[16:17]
	s_mov_b64 s[16:17], 0
	v_lshlrev_b32_e32 v0, 2, v0
	v_lshlrev_b32_e32 v10, 2, v10
	v_lshlrev_b32_e32 v12, 2, v12
	v_lshlrev_b32_e32 v14, 2, v14
	global_load_dwordx4 v[114:117], v[4:5], off offset:0
	global_load_dwordx4 v[118:121], v[4:5], off offset:1024
	global_load_dwordx4 v[122:125], v[4:5], off offset:2048
	global_load_dwordx4 v[126:129], v[4:5], off offset:3072
